# v20 plus the sixteen exec==0 skip branches of the fused-copy store blocks in the sample attention loop removed
# baseline (speedup 1.0000x reference)
.LBB0_1284:
	s_waitcnt vmcnt(15)
	v_cvt_pk_bf16_f32 v40, v112, v113
	v_cvt_pk_bf16_f32 v41, v114, v115
	s_waitcnt vmcnt(13)
	v_cvt_pk_bf16_f32 v44, v104, v105
	v_cvt_pk_bf16_f32 v45, v106, v107
	v_cvt_pk_bf16_f32 v42, v116, v117
	v_cvt_pk_bf16_f32 v43, v118, v119
	ds_write2_b64 v174, v[40:41], v[44:45] offset1:72
	s_waitcnt vmcnt(12)
	v_cvt_pk_bf16_f32 v40, v108, v109
	v_cvt_pk_bf16_f32 v41, v110, v111
	v_add_u32_e32 v204, 0x1000, v174
	ds_write2_b64 v204, v[42:43], v[40:41] offset0:64 offset1:136
	s_waitcnt vmcnt(11)
	v_cvt_pk_bf16_f32 v40, v96, v97
	v_cvt_pk_bf16_f32 v41, v98, v99
	s_waitcnt vmcnt(9)
	v_cvt_pk_bf16_f32 v44, v88, v89
	v_cvt_pk_bf16_f32 v45, v90, v91
	v_cvt_pk_bf16_f32 v42, v100, v101
	v_cvt_pk_bf16_f32 v43, v102, v103
	ds_write2_b64 v174, v[40:41], v[44:45] offset0:144 offset1:216
	s_waitcnt vmcnt(8)
	v_cvt_pk_bf16_f32 v40, v92, v93
	v_cvt_pk_bf16_f32 v41, v94, v95
	v_add_u32_e32 v205, 0x1400, v174
	ds_write2_b64 v205, v[42:43], v[40:41] offset0:80 offset1:152
	s_waitcnt vmcnt(7)
	v_cvt_pk_bf16_f32 v40, v80, v81
	v_cvt_pk_bf16_f32 v41, v82, v83
	s_waitcnt vmcnt(5)
	v_cvt_pk_bf16_f32 v44, v64, v65
	v_cvt_pk_bf16_f32 v45, v66, v67
	v_add_u32_e32 v203, 0x800, v174
	v_cvt_pk_bf16_f32 v42, v84, v85
	v_cvt_pk_bf16_f32 v43, v86, v87
	ds_write2_b64 v203, v[40:41], v[44:45] offset0:32 offset1:104
	s_waitcnt vmcnt(4)
	v_cvt_pk_bf16_f32 v40, v68, v69
	v_cvt_pk_bf16_f32 v41, v70, v71
	v_add_u32_e32 v206, 0x1800, v174
	ds_write2_b64 v206, v[42:43], v[40:41] offset0:96 offset1:168
	s_waitcnt vmcnt(3)
	v_cvt_pk_bf16_f32 v40, v72, v73
	v_cvt_pk_bf16_f32 v41, v74, v75
	s_waitcnt vmcnt(1)
	v_cvt_pk_bf16_f32 v44, v32, v33
	v_cvt_pk_bf16_f32 v45, v34, v35
	ds_write2_b64 v203, v[40:41], v[44:45] offset0:176 offset1:248
	v_cndmask_b32_e64 v44, 0, 1, s[10:11]
	v_cvt_pk_bf16_f32 v42, v76, v77
	v_cvt_pk_bf16_f32 v43, v78, v79
	s_waitcnt vmcnt(0)
	v_cvt_pk_bf16_f32 v40, v36, v37
	v_cvt_pk_bf16_f32 v41, v38, v39
	v_add_u32_e32 v207, 0x1c00, v174
	v_cmp_ne_u32_e64 s[12:13], 1, v44
	s_andn2_b64 vcc, exec, s[10:11]
	ds_write2_b64 v207, v[42:43], v[40:41] offset0:112 offset1:184
	s_cbranch_vccnz .LBB0_1326
	v_add_u32_e32 v41, v199, v201
	v_subrev_u32_e32 v40, 60, v182
	v_add_u32_e32 v42, -8, v41
	v_cmp_ge_i32_e32 vcc, s53, v40
	v_cmp_gt_u32_e64 s[16:17], s92, v42
	s_and_b64 s[16:17], vcc, s[16:17]
	s_and_saveexec_b64 s[82:83], s[16:17]
	s_andn2_b64 vcc, exec, s[8:9]
	s_mov_b64 s[16:17], s[80:81]
	s_cbranch_vccnz .LBB0_1288
	v_cmp_lt_u32_e32 vcc, s93, v41
	v_and_b32_e32 v41, 8, v41
	v_cmp_ne_u32_e64 s[16:17], 0, v41
	s_and_b64 s[16:17], vcc, s[16:17]
	s_andn2_b64 vcc, s[80:81], exec
	s_and_b64 s[16:17], s[16:17], exec
	s_or_b64 s[16:17], vcc, s[16:17]
.LBB0_1288:
	s_and_b64 exec, exec, s[16:17]
	v_add_u32_e32 v120, v156, v200
	v_lshlrev_b64 v[42:43], 2, v[120:121]
	v_lshl_add_u64 v[44:45], v[144:145], 0, v[42:43]
	v_lshl_add_u64 v[42:43], v[146:147], 0, v[42:43]
	global_store_dwordx4 v[44:45], v[112:115], off nt
	global_store_dwordx4 v[42:43], v[116:119], off nt
.LBB0_1290:
	s_or_b64 exec, exec, s[82:83]
	v_add_u32_e32 v41, v183, v201
	v_add_u32_e32 v42, -8, v41
	v_cmp_ge_i32_e32 vcc, s48, v40
	v_cmp_gt_u32_e64 s[16:17], s92, v42
	s_and_b64 s[16:17], vcc, s[16:17]
	s_and_saveexec_b64 s[82:83], s[16:17]
	s_andn2_b64 vcc, exec, s[8:9]
	s_mov_b64 s[16:17], s[80:81]
	s_cbranch_vccnz .LBB0_1293
	v_cmp_lt_u32_e32 vcc, s93, v41
	v_and_b32_e32 v41, 8, v41
	v_cmp_ne_u32_e64 s[16:17], 0, v41
	s_and_b64 s[16:17], vcc, s[16:17]
	s_andn2_b64 vcc, s[80:81], exec
	s_and_b64 s[16:17], s[16:17], exec
	s_or_b64 s[16:17], vcc, s[16:17]
.LBB0_1293:
	s_and_b64 exec, exec, s[16:17]
	v_add_u32_e32 v120, v156, v184
	v_lshlrev_b64 v[42:43], 2, v[120:121]
	v_lshl_add_u64 v[44:45], v[144:145], 0, v[42:43]
	v_lshl_add_u64 v[42:43], v[146:147], 0, v[42:43]
	global_store_dwordx4 v[44:45], v[104:107], off nt
	global_store_dwordx4 v[42:43], v[108:111], off nt
.LBB0_1295:
	s_or_b64 exec, exec, s[82:83]
	v_add_u32_e32 v41, v187, v201
	v_add_u32_e32 v42, -8, v41
	v_cmp_ge_i32_e32 vcc, s49, v40
	v_cmp_gt_u32_e64 s[16:17], s92, v42
	s_and_b64 s[16:17], vcc, s[16:17]
	s_and_saveexec_b64 s[82:83], s[16:17]
	s_andn2_b64 vcc, exec, s[8:9]
	s_mov_b64 s[16:17], s[80:81]
	s_cbranch_vccnz .LBB0_1298
	v_cmp_lt_u32_e32 vcc, s93, v41
	v_and_b32_e32 v41, 8, v41
	v_cmp_ne_u32_e64 s[16:17], 0, v41
	s_and_b64 s[16:17], vcc, s[16:17]
	s_andn2_b64 vcc, s[80:81], exec
	s_and_b64 s[16:17], s[16:17], exec
	s_or_b64 s[16:17], vcc, s[16:17]
.LBB0_1298:
	s_and_b64 exec, exec, s[16:17]
	v_add_u32_e32 v120, v156, v188
	v_lshlrev_b64 v[42:43], 2, v[120:121]
	v_lshl_add_u64 v[44:45], v[144:145], 0, v[42:43]
	v_lshl_add_u64 v[42:43], v[146:147], 0, v[42:43]
	global_store_dwordx4 v[44:45], v[96:99], off nt
	global_store_dwordx4 v[42:43], v[100:103], off nt
.LBB0_1300:
	s_or_b64 exec, exec, s[82:83]
	v_add_u32_e32 v41, v189, v201
	v_add_u32_e32 v42, -8, v41
	v_cmp_ge_i32_e32 vcc, s56, v40
	v_cmp_gt_u32_e64 s[16:17], s92, v42
	s_and_b64 s[16:17], vcc, s[16:17]
	s_and_saveexec_b64 s[82:83], s[16:17]
	s_andn2_b64 vcc, exec, s[8:9]
	s_mov_b64 s[16:17], s[80:81]
	s_cbranch_vccnz .LBB0_1303
	v_cmp_lt_u32_e32 vcc, s93, v41
	v_and_b32_e32 v41, 8, v41
	v_cmp_ne_u32_e64 s[16:17], 0, v41
	s_and_b64 s[16:17], vcc, s[16:17]
	s_andn2_b64 vcc, s[80:81], exec
	s_and_b64 s[16:17], s[16:17], exec
	s_or_b64 s[16:17], vcc, s[16:17]
.LBB0_1303:
	s_and_b64 exec, exec, s[16:17]
	v_add_u32_e32 v120, v156, v190
	v_lshlrev_b64 v[42:43], 2, v[120:121]
	v_lshl_add_u64 v[44:45], v[144:145], 0, v[42:43]
	v_lshl_add_u64 v[42:43], v[146:147], 0, v[42:43]
	global_store_dwordx4 v[44:45], v[88:91], off nt
	global_store_dwordx4 v[42:43], v[92:95], off nt
.LBB0_1305:
	s_or_b64 exec, exec, s[82:83]
	v_add_u32_e32 v41, v191, v201
	v_add_u32_e32 v42, -8, v41
	v_cmp_ge_i32_e32 vcc, s42, v40
	v_cmp_gt_u32_e64 s[16:17], s92, v42
	s_and_b64 s[16:17], vcc, s[16:17]
	s_and_saveexec_b64 s[82:83], s[16:17]
	s_andn2_b64 vcc, exec, s[8:9]
	s_mov_b64 s[16:17], s[80:81]
	s_cbranch_vccnz .LBB0_1308
	v_cmp_lt_u32_e32 vcc, s93, v41
	v_and_b32_e32 v41, 8, v41
	v_cmp_ne_u32_e64 s[16:17], 0, v41
	s_and_b64 s[16:17], vcc, s[16:17]
	s_andn2_b64 vcc, s[80:81], exec
	s_and_b64 s[16:17], s[16:17], exec
	s_or_b64 s[16:17], vcc, s[16:17]
.LBB0_1308:
	s_and_b64 exec, exec, s[16:17]
	v_add_u32_e32 v120, v156, v192
	v_lshlrev_b64 v[42:43], 2, v[120:121]
	v_lshl_add_u64 v[44:45], v[144:145], 0, v[42:43]
	v_lshl_add_u64 v[42:43], v[146:147], 0, v[42:43]
	global_store_dwordx4 v[44:45], v[80:83], off nt
	global_store_dwordx4 v[42:43], v[84:87], off nt
.LBB0_1310:
	s_or_b64 exec, exec, s[82:83]
	v_add_u32_e32 v41, v193, v201
	v_add_u32_e32 v42, -8, v41
	v_cmp_ge_i32_e32 vcc, s54, v40
	v_cmp_gt_u32_e64 s[16:17], s92, v42
	s_and_b64 s[16:17], vcc, s[16:17]
	s_and_saveexec_b64 s[82:83], s[16:17]
	s_andn2_b64 vcc, exec, s[8:9]
	s_mov_b64 s[16:17], s[80:81]
	s_cbranch_vccnz .LBB0_1313
	v_cmp_lt_u32_e32 vcc, s93, v41
	v_and_b32_e32 v41, 8, v41
	v_cmp_ne_u32_e64 s[16:17], 0, v41
	s_and_b64 s[16:17], vcc, s[16:17]
	s_andn2_b64 vcc, s[80:81], exec
	s_and_b64 s[16:17], s[16:17], exec
	s_or_b64 s[16:17], vcc, s[16:17]
.LBB0_1313:
	s_and_b64 exec, exec, s[16:17]
	v_add_u32_e32 v120, v156, v194
	v_lshlrev_b64 v[42:43], 2, v[120:121]
	v_lshl_add_u64 v[44:45], v[144:145], 0, v[42:43]
	v_lshl_add_u64 v[42:43], v[146:147], 0, v[42:43]
	global_store_dwordx4 v[44:45], v[64:67], off nt
	global_store_dwordx4 v[42:43], v[68:71], off nt
.LBB0_1315:
	s_or_b64 exec, exec, s[82:83]
	v_add_u32_e32 v41, v195, v201
	v_add_u32_e32 v42, -8, v41
	v_cmp_ge_i32_e32 vcc, s50, v40
	v_cmp_gt_u32_e64 s[16:17], s92, v42
	s_and_b64 s[16:17], vcc, s[16:17]
	s_and_saveexec_b64 s[82:83], s[16:17]
	s_andn2_b64 vcc, exec, s[8:9]
	s_mov_b64 s[16:17], s[80:81]
	s_cbranch_vccnz .LBB0_1318
	v_cmp_lt_u32_e32 vcc, s93, v41
	v_and_b32_e32 v41, 8, v41
	v_cmp_ne_u32_e64 s[16:17], 0, v41
	s_and_b64 s[16:17], vcc, s[16:17]
	s_andn2_b64 vcc, s[80:81], exec
	s_and_b64 s[16:17], s[16:17], exec
	s_or_b64 s[16:17], vcc, s[16:17]
.LBB0_1318:
	s_and_b64 exec, exec, s[16:17]
	v_add_u32_e32 v120, v156, v196
	v_lshlrev_b64 v[42:43], 2, v[120:121]
	v_lshl_add_u64 v[44:45], v[144:145], 0, v[42:43]
	v_lshl_add_u64 v[42:43], v[146:147], 0, v[42:43]
	global_store_dwordx4 v[44:45], v[72:75], off nt
	global_store_dwordx4 v[42:43], v[76:79], off nt
.LBB0_1320:
	s_or_b64 exec, exec, s[82:83]
	v_add_u32_e32 v41, v197, v201
	v_cmp_ge_i32_e32 vcc, s34, v40
	v_add_u32_e32 v40, -8, v41
	v_cmp_gt_u32_e64 s[16:17], s92, v40
	s_and_b64 s[16:17], vcc, s[16:17]
	s_and_saveexec_b64 s[82:83], s[16:17]
	s_andn2_b64 vcc, exec, s[8:9]
	s_mov_b64 s[16:17], s[80:81]
	s_cbranch_vccnz .LBB0_1323
	v_and_b32_e32 v40, 8, v41
	v_cmp_lt_u32_e32 vcc, s93, v41
	v_cmp_ne_u32_e64 s[16:17], 0, v40
	s_and_b64 s[16:17], vcc, s[16:17]
	s_andn2_b64 vcc, s[80:81], exec
	s_and_b64 s[16:17], s[16:17], exec
	s_or_b64 s[16:17], vcc, s[16:17]
.LBB0_1323:
	s_and_b64 exec, exec, s[16:17]
	v_add_u32_e32 v120, v156, v198
	v_lshlrev_b64 v[40:41], 2, v[120:121]
	v_lshl_add_u64 v[42:43], v[144:145], 0, v[40:41]
	global_store_dwordx4 v[42:43], v[32:35], off nt
	s_nop 1
	v_lshl_add_u64 v[32:33], v[146:147], 0, v[40:41]
	global_store_dwordx4 v[32:33], v[36:39], off nt
